# v77 + chunk-kv LDS read batching: the 4 serialized B-fragment reads of each state MFMA chain issued together with counted lgkmcnt
# speedup vs baseline: 1.0026x; 1.0026x over previous
; #define LAS __attribute__((address_space(3)))
; #define GAS __attribute__((address_space(1)))
; __device__ __forceinline__ int tsw(int d) { return ((d >> 3) & 7) << 3; }
; #define MFMA16(a, b, c) __builtin_amdgcn_mfma_f32_16x16x32_bf16(a, b, c, 0, 0, 0)
; __device__ __forceinline__ void chunkkv_items3(LAS unsigned char* lds, const GAS bf16_t* proj, GAS float* kvT, int it0, int stride, int tid, int w, int lane) {
;     ...
;     const int fr = lane & 15, fq = lane >> 4, et = w >> 1;
; #pragma unroll
;     for (int j = 0; j < 3; ++j) { const int it = it0 + j * stride;
;         if (it < 768) { const int n = it / 6, h = it % 6;
;             const LAS bf16_t* KTs = (const LAS bf16_t*)(lds + j * IMG); const LAS bf16_t* VTs = KTs + 64 * TS;
; #pragma unroll
;             for (int dd = 0; dd < 2; ++dd) { const int dt = 2 * (w & 1) + dd;
;                 f32x4 acc = {0.f, 0.f, 0.f, 0.f};
; #pragma unroll
;                 for (int kc = 0; kc < 4; ++kc) { const bf16x8 a = *(const LAS bf16x8*)(VTs + (16 * et + fr) * TS + ((32 * kc + 8 * fq) ^ tsw(16 * et + fr))), b = *(const LAS bf16x8*)(KTs + (16 * dt + fr) * TS + ((32 * kc + 8 * fq) ^ tsw(16 * dt + fr)));
;                     acc = MFMA16(a, b, acc); }
;                 GAS float* dst = kvT + ((size_t)(n * 6 + h) * 64 + 16 * et + 4 * fq) * 64 + 16 * dt + fr;
; #pragma unroll
;                 for (int i = 0; i < 4; ++i) dst[i * 64] = acc[i];
;             } } }
.LBB0_387:
	s_waitcnt lgkmcnt(0)
	s_barrier
	ds_read_b128 v[2:5], v63 offset:17408
	ds_read_b128 v[6:9], v64
	ds_read_b128 v[10:13], v65 offset:17408
	ds_read_b128 v[14:17], v66
	s_waitcnt lgkmcnt(2)
	v_mfma_f32_16x16x32_bf16 v[6:9], v[2:5], v[6:9], 0
	s_ashr_i32 s1, s0, 31
	s_lshl_b64 s[12:13], s[0:1], 14
	s_and_b64 vcc, exec, s[2:3]
	s_waitcnt lgkmcnt(0)
	v_mfma_f32_16x16x32_bf16 v[6:9], v[10:13], v[14:17], v[6:9]
	ds_read_b128 v[14:17], v67 offset:17408
	ds_read_b128 v[18:21], v68
	s_waitcnt lgkmcnt(0)
	v_mfma_f32_16x16x32_bf16 v[6:9], v[14:17], v[18:21], v[6:9]
	ds_read_b128 v[18:21], v69 offset:17408
	ds_read_b128 v[22:25], v70
	s_waitcnt lgkmcnt(0)
	v_mfma_f32_16x16x32_bf16 v[6:9], v[18:21], v[22:25], v[6:9]
	v_lshl_add_u64 v[22:23], v[52:53], 0, s[12:13]
	s_nop 6
	global_store_dword v[22:23], v6, off
	global_store_dword v[22:23], v7, off offset:256
	global_store_dword v[22:23], v8, off offset:512
	global_store_dword v[22:23], v9, off offset:768
	ds_read_b128 v[196:199], v71
	ds_read_b128 v[200:203], v72
	ds_read_b128 v[204:207], v73
	ds_read_b128 v[208:211], v74
	s_waitcnt lgkmcnt(3)
	v_mfma_f32_16x16x32_bf16 v[2:5], v[2:5], v[196:199], 0
	s_nop 0
	s_waitcnt lgkmcnt(2)
	v_mfma_f32_16x16x32_bf16 v[2:5], v[10:13], v[200:203], v[2:5]
	s_nop 0
	s_waitcnt lgkmcnt(1)
	v_mfma_f32_16x16x32_bf16 v[2:5], v[14:17], v[204:207], v[2:5]
	s_nop 0
	s_waitcnt lgkmcnt(0)
	v_mfma_f32_16x16x32_bf16 v[2:5], v[18:21], v[208:211], v[2:5]
	s_nop 7
	global_store_dword v[22:23], v2, off offset:64
	global_store_dword v[22:23], v3, off offset:320
	global_store_dword v[22:23], v4, off offset:576
	global_store_dword v[22:23], v5, off offset:832
	s_cbranch_vccnz .LBB0_389
	ds_read_b128 v[2:5], v63 offset:52224
	ds_read_b128 v[6:9], v64 offset:34816
	ds_read_b128 v[10:13], v65 offset:52224
	ds_read_b128 v[14:17], v66 offset:34816
	s_ashr_i32 s11, s10, 31
	s_lshl_b64 s[2:3], s[10:11], 14
	s_waitcnt lgkmcnt(2)
	v_mfma_f32_16x16x32_bf16 v[6:9], v[2:5], v[6:9], 0
	s_waitcnt lgkmcnt(0)
	v_mfma_f32_16x16x32_bf16 v[6:9], v[10:13], v[14:17], v[6:9]
	ds_read_b128 v[14:17], v67 offset:52224
	ds_read_b128 v[18:21], v68 offset:34816
	s_waitcnt lgkmcnt(0)
	v_mfma_f32_16x16x32_bf16 v[6:9], v[14:17], v[18:21], v[6:9]
	ds_read_b128 v[18:21], v69 offset:52224
	ds_read_b128 v[22:25], v70 offset:34816
	s_waitcnt lgkmcnt(0)
	v_mfma_f32_16x16x32_bf16 v[6:9], v[18:21], v[22:25], v[6:9]
	v_lshl_add_u64 v[22:23], v[52:53], 0, s[2:3]
	s_nop 6
	global_store_dword v[22:23], v6, off
	global_store_dword v[22:23], v7, off offset:256
	global_store_dword v[22:23], v8, off offset:512
	global_store_dword v[22:23], v9, off offset:768
	ds_read_b128 v[196:199], v71 offset:34816
	ds_read_b128 v[200:203], v72 offset:34816
	ds_read_b128 v[204:207], v73 offset:34816
	ds_read_b128 v[208:211], v74 offset:34816
	s_waitcnt lgkmcnt(3)
	v_mfma_f32_16x16x32_bf16 v[2:5], v[2:5], v[196:199], 0
	s_nop 0
	s_waitcnt lgkmcnt(2)
	v_mfma_f32_16x16x32_bf16 v[2:5], v[10:13], v[200:203], v[2:5]
	s_nop 0
	s_waitcnt lgkmcnt(1)
	v_mfma_f32_16x16x32_bf16 v[2:5], v[14:17], v[204:207], v[2:5]
	s_nop 0
	s_waitcnt lgkmcnt(0)
	v_mfma_f32_16x16x32_bf16 v[2:5], v[18:21], v[208:211], v[2:5]
	s_nop 7
	global_store_dword v[22:23], v2, off offset:64
	global_store_dword v[22:23], v3, off offset:320
	global_store_dword v[22:23], v4, off offset:576
	global_store_dword v[22:23], v5, off offset:832
.LBB0_389:
	s_and_b64 vcc, exec, s[4:5]
	s_cbranch_vccnz .LBB0_378
	ds_read_b128 v[2:5], v75
	ds_read_b128 v[6:9], v76
	ds_read_b128 v[10:13], v77
	ds_read_b128 v[14:17], v78
	s_ashr_i32 s7, s6, 31
	s_lshl_b64 s[2:3], s[6:7], 14
	s_waitcnt lgkmcnt(2)
	v_mfma_f32_16x16x32_bf16 v[6:9], v[2:5], v[6:9], 0
	s_waitcnt lgkmcnt(0)
	v_mfma_f32_16x16x32_bf16 v[6:9], v[10:13], v[14:17], v[6:9]
	ds_read_b128 v[14:17], v79
	ds_read_b128 v[18:21], v80
	s_waitcnt lgkmcnt(0)
	v_mfma_f32_16x16x32_bf16 v[6:9], v[14:17], v[18:21], v[6:9]
	ds_read_b128 v[18:21], v81
	ds_read_b128 v[22:25], v82
	s_waitcnt lgkmcnt(0)
	v_mfma_f32_16x16x32_bf16 v[6:9], v[18:21], v[22:25], v[6:9]
	v_lshl_add_u64 v[22:23], v[52:53], 0, s[2:3]
	s_nop 6
	global_store_dword v[22:23], v6, off
	global_store_dword v[22:23], v7, off offset:256
	global_store_dword v[22:23], v8, off offset:512
	global_store_dword v[22:23], v9, off offset:768
	ds_read_b128 v[196:199], v83
	ds_read_b128 v[200:203], v84
	ds_read_b128 v[204:207], v85
	ds_read_b128 v[208:211], v86
	s_waitcnt lgkmcnt(3)
	v_mfma_f32_16x16x32_bf16 v[2:5], v[2:5], v[196:199], 0
	s_nop 0
	s_waitcnt lgkmcnt(2)
	v_mfma_f32_16x16x32_bf16 v[2:5], v[10:13], v[200:203], v[2:5]
	s_nop 0
	s_waitcnt lgkmcnt(1)
	v_mfma_f32_16x16x32_bf16 v[2:5], v[14:17], v[204:207], v[2:5]
	s_nop 0
	s_waitcnt lgkmcnt(0)
	v_mfma_f32_16x16x32_bf16 v[2:5], v[18:21], v[208:211], v[2:5]
	s_nop 7
	global_store_dword v[22:23], v2, off offset:64
	global_store_dword v[22:23], v3, off offset:320
	global_store_dword v[22:23], v4, off offset:576
	global_store_dword v[22:23], v5, off offset:832
	s_branch .LBB0_378
